# MFMA-LDS interleave in the attention mode-0 unit prologue: the four first-QK fragment ds_reads issued together (v[98:109]) with counted waits
# speedup vs baseline: 1.0067x; 1.0013x over previous
.LBB0_639:
	v_mov_b32_e32 v184, v222
	s_lshl_b32 s2, s0, 2
	v_readfirstlane_b32 s18, v184
	s_ashr_i32 s19, s18, 8
	s_bfe_u32 s22, s18, 0x20006
	s_lshl_b32 s12, s73, 7
	s_or_b32 s2, s2, s74
	s_lshl_b32 s1, s22, 5
	s_lshl_b32 s24, s19, 5
	s_mul_i32 s23, s2, 0x4100
	s_ashr_i32 s25, s12, 31
	s_mul_hi_u32 s13, s2, 0x4100
	s_add_u32 s23, s23, s12
	v_and_b32_e32 v181, 31, v184
	s_addc_u32 s13, s13, s25
	s_or_b32 s23, s23, s1
	v_or_b32_e32 v2, s23, v181
	v_mov_b32_e32 v3, s13
	v_lshlrev_b64 v[2:3], 7, v[2:3]
	v_lshl_add_u64 v[2:3], s[6:7], 0, v[2:3]
	s_ashr_i32 s25, s24, 31
	v_bfe_u32 v180, v184, 5, 1
	v_lshl_add_u64 v[2:3], s[24:25], 1, v[2:3]
	s_mul_i32 s24, s2, 0x208000
	s_mul_hi_u32 s23, s2, 0x208000
	v_lshlrev_b32_e32 v162, 4, v180
	v_mov_b32_e32 v163, v0
	s_add_u32 s26, s11, s24
	v_lshl_add_u64 v[2:3], v[2:3], 0, v[162:163]
	s_addc_u32 s27, s72, s23
	v_ashrrev_i32_e32 v52, 3, v184
	global_load_dwordx4 v[158:161], v[2:3], off
	global_load_dwordx4 v[154:157], v[2:3], off offset:32
	s_add_u32 s28, s36, s24
	v_ashrrev_i32_e32 v53, 31, v52
	v_mov_b64_e32 v[2:3], s[26:27]
	v_lshlrev_b32_e32 v1, 4, v184
	s_addc_u32 s29, s10, s23
	v_lshlrev_b64 v[32:33], 7, v[52:53]
	v_mad_i64_i32 v[2:3], s[26:27], v52, s55, v[2:3]
	v_and_b32_e32 v50, 0x70, v1
	v_mov_b32_e32 v51, v0
	v_lshl_add_u64 v[166:167], v[2:3], 0, v[50:51]
	v_lshl_add_u64 v[2:3], s[28:29], 0, v[32:33]
	v_lshl_add_u64 v[168:169], v[2:3], 0, v[50:51]
	s_nop 1
	v_readfirstlane_b32 s100, v168
	v_readfirstlane_b32 s101, v169
	v_readfirstlane_b32 s98, v166
	v_readfirstlane_b32 s99, v167
	s_nop 1
	v_subrev_u32_e32 v248, s100, v168
	v_subrev_u32_e32 v249, s98, v166
	v_add_co_u32_e32 v46, vcc, s3, v168
	v_mov_b32_e32 v14, v0
	v_mov_b32_e32 v15, v0
	v_addc_co_u32_e32 v47, vcc, 0, v169, vcc
	v_mov_b32_e32 v1, v0
	v_mov_b32_e32 v2, v0
	v_mov_b32_e32 v3, v0
	v_mov_b32_e32 v4, v0
	v_mov_b32_e32 v5, v0
	v_mov_b32_e32 v6, v0
	v_mov_b32_e32 v7, v0
	v_mov_b32_e32 v8, v0
	v_mov_b32_e32 v9, v0
	v_mov_b32_e32 v10, v0
	v_mov_b32_e32 v11, v0
	v_mov_b32_e32 v12, v0
	v_mov_b32_e32 v13, v0
	v_mov_b64_e32 v[30:31], v[14:15]
	v_add_co_u32_e32 v54, vcc, s59, v168
	v_mov_b64_e32 v[28:29], v[12:13]
	v_mov_b64_e32 v[26:27], v[10:11]
	v_mov_b64_e32 v[24:25], v[8:9]
	v_mov_b64_e32 v[22:23], v[6:7]
	v_mov_b64_e32 v[20:21], v[4:5]
	v_mov_b64_e32 v[18:19], v[2:3]
	v_mov_b64_e32 v[16:17], v[0:1]
	v_addc_co_u32_e32 v55, vcc, 0, v169, vcc
	global_load_dwordx4 v[34:37], v[168:169], off
	global_load_dwordx4 v[38:41], v[166:167], off
	global_load_dwordx4 v[42:45], v[166:167], off offset:128
	s_nop 0
	global_load_dwordx4 v[46:49], v[46:47], off
	s_nop 0
	global_load_dwordx4 v[54:57], v[54:55], off
	v_mad_u64_u32 v[164:165], s[26:27], v52, s60, v[50:51]
	v_add_co_u32_e32 v50, vcc, s33, v168
	s_cmp_gt_i32 s73, 1
	v_add_u32_e32 v182, 0, v164
	v_addc_co_u32_e32 v51, vcc, 0, v169, vcc
	s_cselect_b32 s92, 0x8000, s33
	global_load_dwordx4 v[58:61], v[166:167], off offset:256
	global_load_dwordx4 v[62:65], v[50:51], off
	s_cselect_b32 s2, 0x104, 4
	s_mov_b32 s25, 1
	s_add_i32 s13, s2, -1
	s_cmp_lt_i32 s73, 2
	s_barrier
	s_waitcnt vmcnt(5)
	ds_write_b128 v182, v[38:41] offset:36864
	s_waitcnt vmcnt(4)
	ds_write_b128 v182, v[42:45] offset:46080
	ds_write_b128 v182, v[34:37]
	s_waitcnt vmcnt(3)
	ds_write_b128 v182, v[46:49] offset:9216
	s_waitcnt vmcnt(2)
	ds_write_b128 v182, v[54:57] offset:18432
	v_lshl_add_u64 v[34:35], v[168:169], 0, s[92:93]
	s_waitcnt lgkmcnt(0)
	s_barrier
	global_load_dwordx4 v[138:141], v[34:35], off
	global_load_dwordx4 v[142:145], v[166:167], off offset:384
	v_mul_u32_u24_e32 v34, 0x90, v181
	v_add3_u32 v163, 0, v34, v162
	v_lshl_add_u32 v165, s19, 6, v163
	ds_read_b128 v[54:57], v165
	ds_read_b128 v[98:101], v165 offset:4608
	ds_read_b128 v[102:105], v165 offset:32
	ds_read_b128 v[106:109], v165 offset:4640
	s_waitcnt lgkmcnt(3)
	v_mfma_f32_32x32x16_bf16 v[36:51], v[54:57], v[158:161], v[16:31]
	s_waitcnt lgkmcnt(2)
	v_mfma_f32_32x32x16_bf16 v[16:31], v[98:101], v[158:161], v[16:31]
	s_waitcnt lgkmcnt(1)
	v_mfma_f32_32x32x16_bf16 v[36:51], v[102:105], v[154:157], v[36:51]
	v_max3_f32 v34, v36, v37, v38
	s_nop 0
	v_max3_f32 v34, v34, v39, v40
	s_nop 0
	v_max3_f32 v34, v34, v41, v42
	s_nop 0
	v_max3_f32 v34, v34, v43, v44
	s_waitcnt lgkmcnt(0)
	v_mfma_f32_32x32x16_bf16 v[16:31], v[106:109], v[154:157], v[16:31]
	v_max3_f32 v34, v34, v45, v46
	s_nop 0
	v_max3_f32 v34, v34, v47, v48
	s_nop 0
	v_max3_f32 v34, v34, v49, v50
	s_nop 0
	v_max3_f32 v34, v34, v51, v16
	s_nop 0
	v_max3_f32 v34, v34, v17, v18
	s_nop 0
	v_max3_f32 v34, v34, v19, v20
	s_nop 0
	v_max3_f32 v34, v34, v21, v22
	s_nop 0
	v_max3_f32 v34, v34, v23, v24
	s_nop 0
	v_max3_f32 v34, v34, v25, v26
	s_nop 0
	v_max3_f32 v34, v34, v27, v28
	s_nop 0
	v_max3_f32 v34, v34, v29, v30
	s_nop 0
	v_max3_f32 v34, v34, v31, v31
	s_setprio 0
	ds_read_b128 v[54:57], v165 offset:9216
	ds_read_b128 v[106:109], v165 offset:9248
	ds_read_b128 v[110:113], v165 offset:13824
	ds_read_b128 v[114:117], v165 offset:13856
	v_mov_b32_e32 v35, v34
	s_nop 1
	v_permlane32_swap_b32_e32 v34, v35
	v_max_f32_e32 v35, v35, v35
	v_max_f32_e32 v34, v34, v34
	v_max_f32_e32 v35, v34, v35
	v_add_f32_e32 v183, 0, v35
	v_xor_b32_e32 v34, 0x80000000, v183
	v_sub_f32_e32 v53, v36, v35
	v_sub_f32_e32 v16, v16, v35
	v_sub_f32_e32 v66, v37, v35
	v_sub_f32_e32 v17, v17, v35
	v_sub_f32_e32 v67, v38, v35
	v_sub_f32_e32 v18, v18, v35
	v_sub_f32_e32 v68, v39, v35
	v_sub_f32_e32 v19, v19, v35
	v_sub_f32_e32 v69, v40, v35
	v_sub_f32_e32 v20, v20, v35
	v_sub_f32_e32 v70, v41, v35
	v_sub_f32_e32 v21, v21, v35
	v_sub_f32_e32 v71, v42, v35
	v_sub_f32_e32 v22, v22, v35
	v_sub_f32_e32 v72, v43, v35
	v_sub_f32_e32 v23, v23, v35
	v_sub_f32_e32 v118, v44, v35
	v_sub_f32_e32 v24, v24, v35
	v_sub_f32_e32 v119, v45, v35
	v_sub_f32_e32 v25, v25, v35
	v_sub_f32_e32 v120, v46, v35
	v_sub_f32_e32 v26, v26, v35
	v_sub_f32_e32 v121, v47, v35
	v_sub_f32_e32 v27, v27, v35
	v_sub_f32_e32 v122, v48, v35
	v_sub_f32_e32 v28, v28, v35
	v_sub_f32_e32 v123, v49, v35
	v_sub_f32_e32 v29, v29, v35
	v_sub_f32_e32 v50, v50, v35
	v_sub_f32_e32 v30, v30, v35
	v_sub_f32_e32 v51, v51, v35
	v_sub_f32_e32 v31, v31, v35
	v_mov_b32_e32 v35, v34
	v_mov_b32_e32 v36, v34
	v_mov_b32_e32 v37, v34
	v_mov_b32_e32 v38, v34
	v_mov_b32_e32 v39, v34
	v_mov_b32_e32 v40, v34
	v_mov_b32_e32 v41, v34
	v_mov_b32_e32 v42, v34
	v_mov_b32_e32 v43, v34
	v_mov_b32_e32 v44, v34
	v_mov_b32_e32 v45, v34
	v_mov_b32_e32 v46, v34
	v_mov_b32_e32 v47, v34
	v_mov_b32_e32 v48, v34
	v_mov_b32_e32 v49, v34
	s_waitcnt lgkmcnt(3)
	s_nop 4
	v_mfma_f32_32x32x16_bf16 v[82:97], v[54:57], v[158:161], v[34:49]
	v_exp_f32_e32 v102, v53
	v_exp_f32_e32 v103, v66
	v_exp_f32_e32 v104, v67
	v_exp_f32_e32 v105, v68
	s_nop 0
	v_exp_f32_e32 v98, v69
	v_exp_f32_e32 v99, v70
	v_exp_f32_e32 v100, v71
	v_exp_f32_e32 v101, v72
	s_nop 0
	s_waitcnt lgkmcnt(1)
	s_nop 4
	v_mfma_f32_32x32x16_bf16 v[66:81], v[110:113], v[158:161], v[34:49]
	v_exp_f32_e32 v194, v118
	v_exp_f32_e32 v187, v119
	v_exp_f32_e32 v186, v120
	v_exp_f32_e32 v185, v121
	s_nop 0
	v_exp_f32_e32 v133, v122
	v_exp_f32_e32 v132, v123
	v_exp_f32_e32 v131, v50
	v_exp_f32_e32 v130, v51
	s_nop 0
	v_mfma_f32_32x32x16_bf16 v[82:97], v[106:109], v[154:157], v[82:97]
	v_exp_f32_e32 v129, v16
	v_exp_f32_e32 v128, v17
	v_exp_f32_e32 v127, v18
	v_exp_f32_e32 v126, v19
	s_nop 0
	v_exp_f32_e32 v125, v20
	v_exp_f32_e32 v124, v21
	v_exp_f32_e32 v123, v22
	v_exp_f32_e32 v122, v23
	s_nop 0
	s_waitcnt lgkmcnt(0)
	v_mfma_f32_32x32x16_bf16 v[66:81], v[114:117], v[154:157], v[66:81]
	v_exp_f32_e32 v109, v24
	v_exp_f32_e32 v108, v25
	v_exp_f32_e32 v107, v26
	v_exp_f32_e32 v106, v27
	s_nop 0
	v_exp_f32_e32 v113, v28
	v_exp_f32_e32 v112, v29
	v_exp_f32_e32 v111, v30
	v_exp_f32_e32 v110, v31
	s_nop 0
	s_waitcnt vmcnt(2)
	ds_write_b128 v182, v[62:65] offset:27648
	ds_write_b128 v182, v[58:61] offset:55296
	s_cbranch_scc1 .LBB0_665
	s_add_u32 s24, s4, s24
	v_and_b32_e32 v18, 7, v184
	s_addc_u32 s25, s5, s23
	v_mad_i64_i32 v[16:17], s[26:27], v52, s55, 0
	v_lshlrev_b32_e32 v170, 4, v18
	v_lshl_add_u64 v[174:175], s[24:25], 0, v[32:33]
	v_mov_b64_e32 v[32:33], v[14:15]
	v_lshl_add_u64 v[172:173], s[24:25], 0, v[16:17]
	v_mov_b64_e32 v[30:31], v[12:13]
	v_mov_b64_e32 v[28:29], v[10:11]
	v_mov_b64_e32 v[26:27], v[8:9]
	v_mov_b64_e32 v[24:25], v[6:7]
	v_mov_b64_e32 v[22:23], v[4:5]
	v_mov_b64_e32 v[20:21], v[2:3]
	v_mov_b64_e32 v[18:19], v[0:1]
	v_mov_b64_e32 v[16:17], v[14:15]
	v_mov_b32_e32 v171, v0
	s_mov_b32 s25, 1
	v_mov_b32_e32 v50, 0
	s_mov_b32 s23, 12
	v_mov_b64_e32 v[14:15], v[12:13]
	v_mov_b64_e32 v[12:13], v[10:11]
	v_mov_b64_e32 v[10:11], v[8:9]
	v_mov_b64_e32 v[8:9], v[6:7]
	v_mov_b64_e32 v[6:7], v[4:5]
	v_mov_b64_e32 v[4:5], v[2:3]
	v_mov_b64_e32 v[2:3], v[0:1]
